# GATE: norm-weight vectors loaded once per wave before the loop (column segment is loop-invariant), per-item loads and their vmcnt(0) waits removed
# speedup vs baseline: 1.0025x; 1.0025x over previous
; __device__ __forceinline__ float bflo(unsigned w) { return __uint_as_float(w << 16); }
; __device__ __forceinline__ float bfhi(unsigned w) { return __uint_as_float(w & 0xffff0000u); }
; __device__ __forceinline__ float silu_f(float g) { return g * __builtin_amdgcn_rcpf(1.0f + __expf(-g)); }
; __device__ __forceinline__ void gate_phase(const Ctx& c) {
;     const bf16_t* XBC = (const bf16_t*)(c.ws + OFF_XBC); bf16_t* Z = (bf16_t*)(c.ws + OFF_Z);
;     const float* nw = GIN(c, 20);
;     constexpr int NIT = T * 4, U = 4;
;     for (int it0 = c.gw; it0 < NIT; it0 += U * c.ngw) {
;         u32x4 yv[U], zv[U];
; #pragma unroll
;         for (int u = 0; u < U; ++u) {
;             const int it = it0 + u * c.ngw;
;             if (it < NIT) { const int row = it >> 2, col = (it & 3) * 512 + c.lane * 8;
;                 yv[u] = *(const u32x4*)(XBC + (size_t)row * CONVD + col); zv[u] = *(const u32x4*)(Z + (size_t)row * DIN + col); }
;             else { yv[u] = (u32x4){0u, 0u, 0u, 0u}; zv[u] = yv[u]; }
;         }
; #pragma unroll
;         for (int u = 0; u < U; ++u) {
;             const int it = it0 + u * c.ngw;
;             if (it < NIT) {
;                 const int row = it >> 2, col = (it & 3) * 512 + c.lane * 8;
;                 float y[8] = {bflo(yv[u].x), bfhi(yv[u].x), bflo(yv[u].y), bfhi(yv[u].y), bflo(yv[u].z), bfhi(yv[u].z), bflo(yv[u].w), bfhi(yv[u].w)};
;                 const float z[8] = {bflo(zv[u].x), bfhi(zv[u].x), bflo(zv[u].y), bfhi(zv[u].y), bflo(zv[u].z), bfhi(zv[u].z), bflo(zv[u].w), bfhi(zv[u].w)};
;                 float ss = 0.f;
; #pragma unroll
;                 for (int j = 0; j < 8; ++j) { y[j] *= silu_f(z[j]); ss += y[j] * y[j]; }
;                 const float rs = rsqrtf(wave_sum(ss) * (1.0f / 512.0f) + EPS);
;                 const f32x4 n0 = *(const f32x4*)(nw + col), n1 = *(const f32x4*)(nw + col + 4);
.LBB0_111:
	s_cmp_lt_i32 s56, 7
	s_mov_b64 s[2:3], -1
	s_cbranch_scc1 .LBB0_232
	v_readlane_b32 s22, v251, 58
	v_writelane_b32 v254, s88, 16
	v_readlane_b32 s40, v253, 53
	v_readlane_b32 s23, v251, 59
	v_writelane_b32 v254, s89, 17
	s_cmp_gt_i32 s56, 7
	v_readlane_b32 s44, v253, 57
	v_readlane_b32 s45, v253, 58
	v_readlane_b32 s23, v253, 32
	v_readlane_b32 s41, v253, 54
	v_readlane_b32 s42, v253, 55
	v_readlane_b32 s43, v253, 56
	v_readlane_b32 s46, v253, 59
	v_readlane_b32 s47, v253, 60
	v_readlane_b32 s48, v253, 61
	v_readlane_b32 s49, v253, 62
	v_readlane_b32 s50, v253, 63
	v_readlane_b32 s51, v254, 0
	v_readlane_b32 s52, v254, 1
	v_readlane_b32 s53, v254, 2
	v_readlane_b32 s54, v254, 3
	v_readlane_b32 s55, v254, 4
	s_cbranch_scc0 .LBB0_135
	v_readlane_b32 s2, v254, 16
	s_cmp_gt_i32 s2, 0x20fff
	v_readlane_b32 s3, v254, 17
	s_cbranch_scc1 .LBB0_134
	v_and_b32_e32 v0, 64, v234
	v_add_u32_e32 v0, 64, v0
	v_xor_b32_e32 v1, 1, v234
	v_cmp_lt_i32_e32 vcc, v1, v0
	s_add_u32 s12, s90, 0x13488000
	s_addc_u32 s13, s91, 0
	v_cndmask_b32_e32 v1, v234, v1, vcc
	v_lshlrev_b32_e32 v3, 2, v1
	v_xor_b32_e32 v1, 2, v234
	v_cmp_lt_i32_e32 vcc, v1, v0
	s_add_u32 s14, s90, 0xb088000
	s_addc_u32 s15, s91, 0
	v_cndmask_b32_e32 v1, v234, v1, vcc
	v_lshlrev_b32_e32 v36, 2, v1
	v_xor_b32_e32 v1, 4, v234
	v_cmp_lt_i32_e32 vcc, v1, v0
	s_lshl_b32 s2, s92, 9
	v_readlane_b32 s3, v253, 31
	v_cndmask_b32_e32 v1, v234, v1, vcc
	v_lshlrev_b32_e32 v37, 2, v1
	v_xor_b32_e32 v1, 8, v234
	v_cmp_lt_i32_e32 vcc, v1, v0
	s_add_i32 s16, s3, s2
	v_readlane_b32 s2, v254, 16
	v_cndmask_b32_e32 v1, v234, v1, vcc
	v_lshlrev_b32_e32 v38, 2, v1
	v_xor_b32_e32 v1, 16, v234
	v_cmp_lt_i32_e32 vcc, v1, v0
	v_lshlrev_b32_e32 v41, 3, v162
	s_mov_b32 s10, s2
	v_cndmask_b32_e32 v1, v234, v1, vcc
	v_lshlrev_b32_e32 v39, 2, v1
	v_xor_b32_e32 v1, 32, v234
	v_cmp_lt_i32_e32 vcc, v1, v0
	v_readlane_b32 s3, v254, 17
	s_nop 0
	v_cndmask_b32_e32 v0, v234, v1, vcc
	v_lshlrev_b32_e32 v40, 2, v0
	s_and_b32 s4, s16, 0x600
	v_or_b32_e32 v1, s4, v41
	v_lshlrev_b32_e32 v52, 2, v1
	v_readlane_b32 s56, v251, 24
	v_readlane_b32 s57, v251, 25
	s_nop 4
	global_load_dwordx4 v[64:67], v52, s[56:57]
	global_load_dwordx4 v[68:71], v52, s[56:57] offset:16
	s_branch .LBB0_116

; __device__ __forceinline__ unsigned cvt_pk_bf16(float lo, float hi) { f32x2 v = {lo, hi}; bf16x2_t b = __builtin_convertvector(v, bf16x2_t); return __builtin_bit_cast(unsigned, b); }
; __device__ __forceinline__ float bflo(unsigned w) { return __uint_as_float(w << 16); }
; __device__ __forceinline__ float bfhi(unsigned w) { return __uint_as_float(w & 0xffff0000u); }
; __device__ __forceinline__ float silu_f(float g) { return g * __builtin_amdgcn_rcpf(1.0f + __expf(-g)); }
; __device__ __forceinline__ void gate_phase(const Ctx& c) {
;     ...
;         for (int u = 0; u < U; ++u) {
;             const int it = it0 + u * c.ngw;
;             if (it < NIT) {
;                 const int row = it >> 2, col = (it & 3) * 512 + c.lane * 8;
;                 float y[8] = {bflo(yv[u].x), bfhi(yv[u].x), bflo(yv[u].y), bfhi(yv[u].y), bflo(yv[u].z), bfhi(yv[u].z), bflo(yv[u].w), bfhi(yv[u].w)};
;                 const float z[8] = {bflo(zv[u].x), bfhi(zv[u].x), bflo(zv[u].y), bfhi(zv[u].y), bflo(zv[u].z), bfhi(zv[u].z), bflo(zv[u].w), bfhi(zv[u].w)};
;                 float ss = 0.f;
; #pragma unroll
;                 for (int j = 0; j < 8; ++j) { y[j] *= silu_f(z[j]); ss += y[j] * y[j]; }
;                 const float rs = rsqrtf(wave_sum(ss) * (1.0f / 512.0f) + EPS);
;                 const f32x4 n0 = *(const f32x4*)(nw + col), n1 = *(const f32x4*)(nw + col + 4);
;                 u32x4 o; o.x = cvt_pk_bf16(y[0] * rs * n0[0], y[1] * rs * n0[1]); o.y = cvt_pk_bf16(y[2] * rs * n0[2], y[3] * rs * n0[3]);
;                 o.z = cvt_pk_bf16(y[4] * rs * n1[0], y[5] * rs * n1[1]); o.w = cvt_pk_bf16(y[6] * rs * n1[2], y[7] * rs * n1[3]);
;                 *(u32x4*)(Z + (size_t)row * DIN + col) = o;
.LBB0_128:
	s_waitcnt vmcnt(0)
	v_lshlrev_b32_e32 v50, 16, v35
	v_and_b32_e32 v51, 0xffff0000, v35
	v_mul_f32_e32 v35, 0xbfb8aa3b, v50
	v_exp_f32_e32 v35, v35
	v_mul_f32_e32 v42, 0xbfb8aa3b, v51
	v_exp_f32_e32 v42, v42
	v_lshlrev_b32_e32 v52, 2, v1
	v_add_f32_e32 v1, 1.0, v35
	v_rcp_f32_e32 v54, v1
	v_add_f32_e32 v1, 1.0, v42
	v_rcp_f32_e32 v55, v1
	v_lshlrev_b32_e32 v56, 16, v31
	v_and_b32_e32 v57, 0xffff0000, v31
	v_readlane_b32 s48, v251, 16
	v_pk_mul_f32 v[50:51], v[54:55], v[50:51]
	v_lshlrev_b32_e32 v54, 16, v34
	v_and_b32_e32 v55, 0xffff0000, v34
	v_mul_f32_e32 v1, 0xbfb8aa3b, v54
	v_exp_f32_e32 v1, v1
	v_mul_f32_e32 v31, 0xbfb8aa3b, v55
	v_exp_f32_e32 v31, v31
	v_pk_mul_f32 v[34:35], v[50:51], v[56:57]
	v_add_f32_e32 v1, 1.0, v1
	v_rcp_f32_e32 v50, v1
	v_add_f32_e32 v1, 1.0, v31
	v_rcp_f32_e32 v51, v1
	v_readlane_b32 s56, v251, 24
	v_readlane_b32 s57, v251, 25
	s_nop 4
	v_lshlrev_b32_e32 v58, 16, v30
	v_and_b32_e32 v59, 0xffff0000, v30
	v_pk_mul_f32 v[30:31], v[50:51], v[54:55]
	v_lshlrev_b32_e32 v50, 16, v33
	v_and_b32_e32 v51, 0xffff0000, v33
	v_mul_f32_e32 v1, 0xbfb8aa3b, v50
	v_exp_f32_e32 v1, v1
	v_mul_f32_e32 v33, 0xbfb8aa3b, v51
	v_exp_f32_e32 v33, v33
	v_pk_mul_f32 v[54:55], v[30:31], v[58:59]
	v_add_f32_e32 v1, 1.0, v1
	v_rcp_f32_e32 v30, v1
	v_add_f32_e32 v1, 1.0, v33
	v_rcp_f32_e32 v31, v1
	v_lshlrev_b32_e32 v60, 16, v29
	v_and_b32_e32 v61, 0xffff0000, v29
	v_lshlrev_b32_e32 v62, 16, v28
	v_pk_mul_f32 v[30:31], v[30:31], v[50:51]
	v_lshlrev_b32_e32 v50, 16, v32
	v_and_b32_e32 v51, 0xffff0000, v32
	v_mul_f32_e32 v1, 0xbfb8aa3b, v50
	v_exp_f32_e32 v1, v1
	v_mul_f32_e32 v29, 0xbfb8aa3b, v51
	v_exp_f32_e32 v29, v29
	v_pk_mul_f32 v[32:33], v[30:31], v[60:61]
	v_add_f32_e32 v1, 1.0, v1
	v_rcp_f32_e32 v30, v1
	v_add_f32_e32 v1, 1.0, v29
	v_rcp_f32_e32 v31, v1
	v_and_b32_e32 v63, 0xffff0000, v28
	v_pk_mul_f32 v[60:61], v[32:33], v[32:33]
	v_pk_mul_f32 v[58:59], v[54:55], v[54:55]
	v_pk_mul_f32 v[28:29], v[30:31], v[50:51]
	v_pk_mul_f32 v[56:57], v[34:35], v[34:35]
	v_pk_mul_f32 v[30:31], v[28:29], v[62:63]
	v_mov_b32_e32 v53, v2
	v_pk_mul_f32 v[28:29], v[30:31], v[30:31]
	v_readlane_b32 s49, v251, 17
	v_add_f32_e32 v1, v28, v29
	v_add_f32_e32 v1, v60, v1
	v_add_f32_e32 v1, v61, v1
	v_add_f32_e32 v1, v58, v1
	v_add_f32_e32 v1, v59, v1
	v_add_f32_e32 v1, v56, v1
	v_add_f32_e32 v1, v57, v1
	s_nop 1
	v_add_f32_dpp v28, v1, v1 quad_perm:[1,0,3,2] row_mask:0xf bank_mask:0xf
	s_nop 1
	v_add_f32_dpp v28, v28, v28 quad_perm:[2,3,0,1] row_mask:0xf bank_mask:0xf
	s_nop 1
	v_add_f32_dpp v28, v28, v28 row_half_mirror row_mask:0xf bank_mask:0xf
	s_nop 1
	v_add_f32_dpp v28, v28, v28 row_mirror row_mask:0xf bank_mask:0xf
	s_nop 1
	v_add_f32_dpp v28, v28, v28 row_bcast:15 row_mask:0xa bank_mask:0xf
	s_nop 1
	v_add_f32_dpp v28, v28, v28 row_bcast:31 row_mask:0xc bank_mask:0xf
	s_nop 0
	v_readlane_b32 s32, v28, 63
	s_nop 1
	v_mov_b32_e32 v28, s32
	v_readlane_b32 s50, v251, 18
	v_readlane_b32 s51, v251, 19
	v_readlane_b32 s52, v251, 20
	v_readlane_b32 s53, v251, 21
	v_readlane_b32 s54, v251, 22
	v_readlane_b32 s55, v251, 23
	v_readlane_b32 s58, v251, 26
	v_readlane_b32 s59, v251, 27
	v_readlane_b32 s60, v251, 28
	v_readlane_b32 s61, v251, 29
	v_readlane_b32 s62, v251, 30
	v_readlane_b32 s63, v251, 31
	v_mov_b32_e32 v1, v2
	v_lshl_add_u64 v[50:51], s[8:9], 0, v[0:1]
	v_fmamk_f32 v28, v28, 0x3b000000, v228
	v_mul_f32_e32 v29, 0x4b800000, v28
	v_cmp_gt_f32_e32 vcc, s37, v28
	s_nop 1
	v_cndmask_b32_e32 v28, v28, v29, vcc
	v_rsq_f32_e32 v56, v28
	v_lshl_add_u64 v[28:29], s[56:57], 0, v[52:53]
	v_mul_f32_e32 v1, 0x45800000, v56
	v_cndmask_b32_e32 v52, v56, v1, vcc
	v_pk_mul_f32 v[30:31], v[30:31], v[52:53] op_sel_hi:[1,0]
	v_pk_mul_f32 v[32:33], v[32:33], v[52:53] op_sel_hi:[1,0]
	v_pk_mul_f32 v[30:31], v[64:65], v[30:31]
	v_pk_mul_f32 v[32:33], v[66:67], v[32:33]
	v_cvt_pk_bf16_f32 v30, v30, v31
	v_cvt_pk_bf16_f32 v31, v32, v33
	v_pk_mul_f32 v[32:33], v[54:55], v[52:53] op_sel_hi:[1,0]
	v_pk_mul_f32 v[34:35], v[34:35], v[52:53] op_sel_hi:[1,0]
	v_pk_mul_f32 v[32:33], v[68:69], v[32:33]
	v_pk_mul_f32 v[34:35], v[70:71], v[34:35]
	v_cvt_pk_bf16_f32 v32, v32, v33
	v_cvt_pk_bf16_f32 v33, v34, v35
	s_andn2_b64 vcc, exec, s[6:7]
	global_store_dwordx4 v[50:51], v[30:33], off
	s_cbranch_vccnz .LBB0_131
; __device__ __forceinline__ unsigned cvt_pk_bf16(float lo, float hi) { f32x2 v = {lo, hi}; bf16x2_t b = __builtin_convertvector(v, bf16x2_t); return __builtin_bit_cast(unsigned, b); }
; __device__ __forceinline__ float bflo(unsigned w) { return __uint_as_float(w << 16); }
; __device__ __forceinline__ float bfhi(unsigned w) { return __uint_as_float(w & 0xffff0000u); }
; __device__ __forceinline__ float silu_f(float g) { return g * __builtin_amdgcn_rcpf(1.0f + __expf(-g)); }
; __device__ __forceinline__ void gate_phase(const Ctx& c) {
;     ...
;         for (int u = 0; u < U; ++u) {
;             const int it = it0 + u * c.ngw;
;             if (it < NIT) {
;                 const int row = it >> 2, col = (it & 3) * 512 + c.lane * 8;
;                 float y[8] = {bflo(yv[u].x), bfhi(yv[u].x), bflo(yv[u].y), bfhi(yv[u].y), bflo(yv[u].z), bfhi(yv[u].z), bflo(yv[u].w), bfhi(yv[u].w)};
;                 const float z[8] = {bflo(zv[u].x), bfhi(zv[u].x), bflo(zv[u].y), bfhi(zv[u].y), bflo(zv[u].z), bfhi(zv[u].z), bflo(zv[u].w), bfhi(zv[u].w)};
;                 float ss = 0.f;
; #pragma unroll
;                 for (int j = 0; j < 8; ++j) { y[j] *= silu_f(z[j]); ss += y[j] * y[j]; }
;                 const float rs = rsqrtf(wave_sum(ss) * (1.0f / 512.0f) + EPS);
;                 const f32x4 n0 = *(const f32x4*)(nw + col), n1 = *(const f32x4*)(nw + col + 4);
;                 u32x4 o; o.x = cvt_pk_bf16(y[0] * rs * n0[0], y[1] * rs * n0[1]); o.y = cvt_pk_bf16(y[2] * rs * n0[2], y[3] * rs * n0[3]);
;                 o.z = cvt_pk_bf16(y[4] * rs * n1[0], y[5] * rs * n1[1]); o.w = cvt_pk_bf16(y[6] * rs * n1[2], y[7] * rs * n1[3]);
;                 *(u32x4*)(Z + (size_t)row * DIN + col) = o;
	v_lshlrev_b32_e32 v34, 16, v27
	v_and_b32_e32 v35, 0xffff0000, v27
	v_mul_f32_e32 v1, 0xbfb8aa3b, v34
	v_exp_f32_e32 v1, v1
	v_mul_f32_e32 v27, 0xbfb8aa3b, v35
	v_exp_f32_e32 v27, v27
	v_lshlrev_b32_e32 v48, 16, v23
	v_add_f32_e32 v1, 1.0, v1
	v_rcp_f32_e32 v46, v1
	v_add_f32_e32 v1, 1.0, v27
	v_rcp_f32_e32 v47, v1
	v_and_b32_e32 v49, 0xffff0000, v23
	v_lshlrev_b32_e32 v50, 16, v22
	v_pk_mul_f32 v[34:35], v[46:47], v[34:35]
	v_lshlrev_b32_e32 v46, 16, v26
	v_and_b32_e32 v47, 0xffff0000, v26
	v_mul_f32_e32 v1, 0xbfb8aa3b, v46
	v_exp_f32_e32 v1, v1
	v_mul_f32_e32 v23, 0xbfb8aa3b, v47
	v_exp_f32_e32 v23, v23
	v_pk_mul_f32 v[26:27], v[34:35], v[48:49]
	v_add_f32_e32 v1, 1.0, v1
	v_rcp_f32_e32 v34, v1
	v_add_f32_e32 v1, 1.0, v23
	v_rcp_f32_e32 v35, v1
	v_and_b32_e32 v51, 0xffff0000, v22
	v_lshlrev_b32_e32 v52, 16, v21
	v_and_b32_e32 v53, 0xffff0000, v21
	v_pk_mul_f32 v[22:23], v[34:35], v[46:47]
	v_lshlrev_b32_e32 v34, 16, v25
	v_and_b32_e32 v35, 0xffff0000, v25
	v_mul_f32_e32 v1, 0xbfb8aa3b, v34
	v_exp_f32_e32 v1, v1
	v_mul_f32_e32 v25, 0xbfb8aa3b, v35
	v_exp_f32_e32 v25, v25
	v_lshlrev_b32_e32 v54, 16, v20
	v_add_f32_e32 v1, 1.0, v1
	v_rcp_f32_e32 v46, v1
	v_add_f32_e32 v1, 1.0, v25
	v_rcp_f32_e32 v47, v1
	v_and_b32_e32 v55, 0xffff0000, v20
	v_pk_mul_f32 v[22:23], v[22:23], v[50:51]
	v_pk_mul_f32 v[48:49], v[26:27], v[26:27]
	v_pk_mul_f32 v[34:35], v[46:47], v[34:35]
	v_lshlrev_b32_e32 v46, 16, v24
	v_and_b32_e32 v47, 0xffff0000, v24
	v_mul_f32_e32 v1, 0xbfb8aa3b, v46
	v_exp_f32_e32 v1, v1
	v_mul_f32_e32 v21, 0xbfb8aa3b, v47
	v_exp_f32_e32 v21, v21
	v_pk_mul_f32 v[24:25], v[34:35], v[52:53]
	v_add_f32_e32 v1, 1.0, v1
	v_rcp_f32_e32 v34, v1
	v_add_f32_e32 v1, 1.0, v21
	v_rcp_f32_e32 v35, v1
	v_pk_mul_f32 v[52:53], v[24:25], v[24:25]
	v_pk_mul_f32 v[50:51], v[22:23], v[22:23]
	s_ashr_i32 s6, s17, 2
	v_pk_mul_f32 v[20:21], v[34:35], v[46:47]
	s_ashr_i32 s7, s6, 31
	v_pk_mul_f32 v[20:21], v[20:21], v[54:55]
	s_lshl_b64 s[6:7], s[6:7], 12
	v_pk_mul_f32 v[34:35], v[20:21], v[20:21]
	s_add_u32 s6, s14, s6
	v_add_f32_e32 v1, v34, v35
	v_add_f32_e32 v1, v52, v1
	v_add_f32_e32 v1, v53, v1
	v_add_f32_e32 v1, v50, v1
	v_add_f32_e32 v1, v51, v1
	v_add_f32_e32 v1, v48, v1
	v_add_f32_e32 v1, v49, v1
	s_nop 1
	v_add_f32_dpp v1, v1, v1 quad_perm:[1,0,3,2] row_mask:0xf bank_mask:0xf
	s_nop 1
	v_add_f32_dpp v1, v1, v1 quad_perm:[2,3,0,1] row_mask:0xf bank_mask:0xf
	s_nop 1
	v_add_f32_dpp v1, v1, v1 row_half_mirror row_mask:0xf bank_mask:0xf
	s_nop 1
	v_add_f32_dpp v1, v1, v1 row_mirror row_mask:0xf bank_mask:0xf
	s_nop 1
	v_add_f32_dpp v1, v1, v1 row_bcast:15 row_mask:0xa bank_mask:0xf
	s_nop 1
	v_add_f32_dpp v1, v1, v1 row_bcast:31 row_mask:0xc bank_mask:0xf
	s_nop 0
	v_readlane_b32 s32, v1, 63
	s_nop 1
	v_mov_b32_e32 v1, s32
	s_addc_u32 s7, s15, s7
	v_fmamk_f32 v1, v1, 0x3b000000, v228
	v_mul_f32_e32 v34, 0x4b800000, v1
	v_cmp_gt_f32_e32 vcc, s37, v1
	s_nop 1
	v_cndmask_b32_e32 v1, v1, v34, vcc
	v_rsq_f32_e32 v1, v1
	s_nop 0
	v_mul_f32_e32 v34, 0x45800000, v1
	v_cndmask_b32_e32 v34, v1, v34, vcc
	v_pk_mul_f32 v[20:21], v[20:21], v[34:35] op_sel_hi:[1,0]
	v_pk_mul_f32 v[24:25], v[24:25], v[34:35] op_sel_hi:[1,0]
	v_pk_mul_f32 v[20:21], v[64:65], v[20:21]
	v_pk_mul_f32 v[24:25], v[66:67], v[24:25]
	v_cvt_pk_bf16_f32 v20, v20, v21
	v_cvt_pk_bf16_f32 v21, v24, v25
	v_pk_mul_f32 v[22:23], v[22:23], v[34:35] op_sel_hi:[1,0]
	v_pk_mul_f32 v[24:25], v[26:27], v[34:35] op_sel_hi:[1,0]
	v_pk_mul_f32 v[22:23], v[68:69], v[22:23]
	v_pk_mul_f32 v[24:25], v[70:71], v[24:25]
	v_cvt_pk_bf16_f32 v22, v22, v23
	v_cvt_pk_bf16_f32 v23, v24, v25
	global_store_dwordx4 v0, v[20:23], s[6:7]
	s_andn2_b64 vcc, exec, s[4:5]
	s_cbranch_vccz .LBB0_132

; __device__ __forceinline__ unsigned cvt_pk_bf16(float lo, float hi) { f32x2 v = {lo, hi}; bf16x2_t b = __builtin_convertvector(v, bf16x2_t); return __builtin_bit_cast(unsigned, b); }
; __device__ __forceinline__ float bflo(unsigned w) { return __uint_as_float(w << 16); }
; __device__ __forceinline__ float bfhi(unsigned w) { return __uint_as_float(w & 0xffff0000u); }
; __device__ __forceinline__ float silu_f(float g) { return g * __builtin_amdgcn_rcpf(1.0f + __expf(-g)); }
; __device__ __forceinline__ void gate_phase(const Ctx& c) {
;     ...
;         for (int u = 0; u < U; ++u) {
;             const int it = it0 + u * c.ngw;
;             if (it < NIT) {
;                 const int row = it >> 2, col = (it & 3) * 512 + c.lane * 8;
;                 float y[8] = {bflo(yv[u].x), bfhi(yv[u].x), bflo(yv[u].y), bfhi(yv[u].y), bflo(yv[u].z), bfhi(yv[u].z), bflo(yv[u].w), bfhi(yv[u].w)};
;                 const float z[8] = {bflo(zv[u].x), bfhi(zv[u].x), bflo(zv[u].y), bfhi(zv[u].y), bflo(zv[u].z), bfhi(zv[u].z), bflo(zv[u].w), bfhi(zv[u].w)};
;                 float ss = 0.f;
; #pragma unroll
;                 for (int j = 0; j < 8; ++j) { y[j] *= silu_f(z[j]); ss += y[j] * y[j]; }
;                 const float rs = rsqrtf(wave_sum(ss) * (1.0f / 512.0f) + EPS);
;                 const f32x4 n0 = *(const f32x4*)(nw + col), n1 = *(const f32x4*)(nw + col + 4);
;                 u32x4 o; o.x = cvt_pk_bf16(y[0] * rs * n0[0], y[1] * rs * n0[1]); o.y = cvt_pk_bf16(y[2] * rs * n0[2], y[3] * rs * n0[3]);
;                 o.z = cvt_pk_bf16(y[4] * rs * n1[0], y[5] * rs * n1[1]); o.w = cvt_pk_bf16(y[6] * rs * n1[2], y[7] * rs * n1[3]);
;                 *(u32x4*)(Z + (size_t)row * DIN + col) = o;
.LBB0_132:
	v_lshlrev_b32_e32 v30, 16, v19
	v_and_b32_e32 v31, 0xffff0000, v19
	v_mul_f32_e32 v1, 0xbfb8aa3b, v30
	v_exp_f32_e32 v1, v1
	v_mul_f32_e32 v19, 0xbfb8aa3b, v31
	v_exp_f32_e32 v19, v19
	v_lshlrev_b32_e32 v34, 16, v15
	v_add_f32_e32 v1, 1.0, v1
	v_rcp_f32_e32 v32, v1
	v_add_f32_e32 v1, 1.0, v19
	v_rcp_f32_e32 v33, v1
	v_and_b32_e32 v35, 0xffff0000, v15
	v_lshlrev_b32_e32 v42, 16, v14
	v_pk_mul_f32 v[30:31], v[32:33], v[30:31]
	v_lshlrev_b32_e32 v32, 16, v18
	v_and_b32_e32 v33, 0xffff0000, v18
	v_mul_f32_e32 v1, 0xbfb8aa3b, v32
	v_exp_f32_e32 v1, v1
	v_mul_f32_e32 v15, 0xbfb8aa3b, v33
	v_exp_f32_e32 v15, v15
	v_pk_mul_f32 v[18:19], v[30:31], v[34:35]
	v_add_f32_e32 v1, 1.0, v1
	v_rcp_f32_e32 v30, v1
	v_add_f32_e32 v1, 1.0, v15
	v_rcp_f32_e32 v31, v1
	v_and_b32_e32 v43, 0xffff0000, v14
	v_lshlrev_b32_e32 v44, 16, v13
	v_and_b32_e32 v45, 0xffff0000, v13
	v_pk_mul_f32 v[14:15], v[30:31], v[32:33]
	v_lshlrev_b32_e32 v30, 16, v17
	v_and_b32_e32 v31, 0xffff0000, v17
	v_mul_f32_e32 v1, 0xbfb8aa3b, v30
	v_exp_f32_e32 v1, v1
	v_mul_f32_e32 v17, 0xbfb8aa3b, v31
	v_exp_f32_e32 v17, v17
	v_lshlrev_b32_e32 v46, 16, v12
	v_add_f32_e32 v1, 1.0, v1
	v_rcp_f32_e32 v32, v1
	v_add_f32_e32 v1, 1.0, v17
	v_rcp_f32_e32 v33, v1
	v_and_b32_e32 v47, 0xffff0000, v12
	v_pk_mul_f32 v[14:15], v[14:15], v[42:43]
	v_pk_mul_f32 v[34:35], v[18:19], v[18:19]
	v_pk_mul_f32 v[30:31], v[32:33], v[30:31]
	v_lshlrev_b32_e32 v32, 16, v16
	v_and_b32_e32 v33, 0xffff0000, v16
	v_mul_f32_e32 v1, 0xbfb8aa3b, v32
	v_exp_f32_e32 v1, v1
	v_mul_f32_e32 v13, 0xbfb8aa3b, v33
	v_exp_f32_e32 v13, v13
	v_pk_mul_f32 v[16:17], v[30:31], v[44:45]
	v_add_f32_e32 v1, 1.0, v1
	v_rcp_f32_e32 v30, v1
	v_add_f32_e32 v1, 1.0, v13
	v_rcp_f32_e32 v31, v1
	v_pk_mul_f32 v[44:45], v[16:17], v[16:17]
	v_pk_mul_f32 v[42:43], v[14:15], v[14:15]
	s_ashr_i32 s4, s19, 2
	v_pk_mul_f32 v[12:13], v[30:31], v[32:33]
	s_ashr_i32 s5, s4, 31
	v_pk_mul_f32 v[12:13], v[12:13], v[46:47]
	s_lshl_b64 s[4:5], s[4:5], 12
	v_pk_mul_f32 v[30:31], v[12:13], v[12:13]
	s_add_u32 s4, s14, s4
	v_add_f32_e32 v1, v30, v31
	v_add_f32_e32 v1, v44, v1
	v_add_f32_e32 v1, v45, v1
	v_add_f32_e32 v1, v42, v1
	v_add_f32_e32 v1, v43, v1
	v_add_f32_e32 v1, v34, v1
	v_add_f32_e32 v1, v35, v1
	s_nop 1
	v_add_f32_dpp v1, v1, v1 quad_perm:[1,0,3,2] row_mask:0xf bank_mask:0xf
	s_nop 1
	v_add_f32_dpp v1, v1, v1 quad_perm:[2,3,0,1] row_mask:0xf bank_mask:0xf
	s_nop 1
	v_add_f32_dpp v1, v1, v1 row_half_mirror row_mask:0xf bank_mask:0xf
	s_nop 1
	v_add_f32_dpp v1, v1, v1 row_mirror row_mask:0xf bank_mask:0xf
	s_nop 1
	v_add_f32_dpp v1, v1, v1 row_bcast:15 row_mask:0xa bank_mask:0xf
	s_nop 1
	v_add_f32_dpp v1, v1, v1 row_bcast:31 row_mask:0xc bank_mask:0xf
	s_nop 0
	v_readlane_b32 s32, v1, 63
	s_nop 1
	v_mov_b32_e32 v1, s32
	s_addc_u32 s5, s15, s5
	v_fmamk_f32 v1, v1, 0x3b000000, v228
	v_mul_f32_e32 v30, 0x4b800000, v1
	v_cmp_gt_f32_e32 vcc, s37, v1
	s_nop 1
	v_cndmask_b32_e32 v1, v1, v30, vcc
	v_rsq_f32_e32 v1, v1
	s_nop 0
	v_mul_f32_e32 v30, 0x45800000, v1
	v_cndmask_b32_e32 v30, v1, v30, vcc
	v_pk_mul_f32 v[12:13], v[12:13], v[30:31] op_sel_hi:[1,0]
	v_pk_mul_f32 v[16:17], v[16:17], v[30:31] op_sel_hi:[1,0]
	v_pk_mul_f32 v[12:13], v[64:65], v[12:13]
	v_pk_mul_f32 v[16:17], v[66:67], v[16:17]
	v_cvt_pk_bf16_f32 v12, v12, v13
	v_cvt_pk_bf16_f32 v13, v16, v17
	v_pk_mul_f32 v[14:15], v[14:15], v[30:31] op_sel_hi:[1,0]
	v_pk_mul_f32 v[16:17], v[18:19], v[30:31] op_sel_hi:[1,0]
	v_pk_mul_f32 v[14:15], v[68:69], v[14:15]
	v_pk_mul_f32 v[16:17], v[70:71], v[16:17]
	v_cvt_pk_bf16_f32 v14, v14, v15
	v_cvt_pk_bf16_f32 v15, v16, v17
	global_store_dwordx4 v0, v[12:15], s[4:5]
	s_andn2_b64 vcc, exec, s[2:3]
	s_cbranch_vccnz .LBB0_115
; __device__ __forceinline__ unsigned cvt_pk_bf16(float lo, float hi) { f32x2 v = {lo, hi}; bf16x2_t b = __builtin_convertvector(v, bf16x2_t); return __builtin_bit_cast(unsigned, b); }
; __device__ __forceinline__ float bflo(unsigned w) { return __uint_as_float(w << 16); }
; __device__ __forceinline__ float bfhi(unsigned w) { return __uint_as_float(w & 0xffff0000u); }
; __device__ __forceinline__ float silu_f(float g) { return g * __builtin_amdgcn_rcpf(1.0f + __expf(-g)); }
; __device__ __forceinline__ void gate_phase(const Ctx& c) {
;     ...
;         for (int u = 0; u < U; ++u) {
;             const int it = it0 + u * c.ngw;
;             if (it < NIT) {
;                 const int row = it >> 2, col = (it & 3) * 512 + c.lane * 8;
;                 float y[8] = {bflo(yv[u].x), bfhi(yv[u].x), bflo(yv[u].y), bfhi(yv[u].y), bflo(yv[u].z), bfhi(yv[u].z), bflo(yv[u].w), bfhi(yv[u].w)};
;                 const float z[8] = {bflo(zv[u].x), bfhi(zv[u].x), bflo(zv[u].y), bfhi(zv[u].y), bflo(zv[u].z), bfhi(zv[u].z), bflo(zv[u].w), bfhi(zv[u].w)};
;                 float ss = 0.f;
; #pragma unroll
;                 for (int j = 0; j < 8; ++j) { y[j] *= silu_f(z[j]); ss += y[j] * y[j]; }
;                 const float rs = rsqrtf(wave_sum(ss) * (1.0f / 512.0f) + EPS);
;                 const f32x4 n0 = *(const f32x4*)(nw + col), n1 = *(const f32x4*)(nw + col + 4);
;                 u32x4 o; o.x = cvt_pk_bf16(y[0] * rs * n0[0], y[1] * rs * n0[1]); o.y = cvt_pk_bf16(y[2] * rs * n0[2], y[3] * rs * n0[3]);
;                 o.z = cvt_pk_bf16(y[4] * rs * n1[0], y[5] * rs * n1[1]); o.w = cvt_pk_bf16(y[6] * rs * n1[2], y[7] * rs * n1[3]);
;                 *(u32x4*)(Z + (size_t)row * DIN + col) = o;
.LBB0_133:
	v_lshlrev_b32_e32 v20, 16, v11
	v_and_b32_e32 v21, 0xffff0000, v11
	v_mul_f32_e32 v1, 0xbfb8aa3b, v20
	v_exp_f32_e32 v1, v1
	v_mul_f32_e32 v11, 0xbfb8aa3b, v21
	v_exp_f32_e32 v11, v11
	v_lshlrev_b32_e32 v24, 16, v7
	v_add_f32_e32 v1, 1.0, v1
	v_rcp_f32_e32 v22, v1
	v_add_f32_e32 v1, 1.0, v11
	v_rcp_f32_e32 v23, v1
	v_and_b32_e32 v25, 0xffff0000, v7
	v_lshlrev_b32_e32 v26, 16, v6
	v_pk_mul_f32 v[20:21], v[22:23], v[20:21]
	v_lshlrev_b32_e32 v22, 16, v10
	v_and_b32_e32 v23, 0xffff0000, v10
	v_mul_f32_e32 v1, 0xbfb8aa3b, v22
	v_exp_f32_e32 v1, v1
	v_mul_f32_e32 v7, 0xbfb8aa3b, v23
	v_exp_f32_e32 v7, v7
	v_pk_mul_f32 v[10:11], v[20:21], v[24:25]
	v_add_f32_e32 v1, 1.0, v1
	v_rcp_f32_e32 v20, v1
	v_add_f32_e32 v1, 1.0, v7
	v_rcp_f32_e32 v21, v1
	v_and_b32_e32 v27, 0xffff0000, v6
	v_lshlrev_b32_e32 v28, 16, v5
	v_and_b32_e32 v29, 0xffff0000, v5
	v_pk_mul_f32 v[6:7], v[20:21], v[22:23]
	v_lshlrev_b32_e32 v20, 16, v9
	v_and_b32_e32 v21, 0xffff0000, v9
	v_mul_f32_e32 v1, 0xbfb8aa3b, v20
	v_exp_f32_e32 v1, v1
	v_mul_f32_e32 v9, 0xbfb8aa3b, v21
	v_exp_f32_e32 v9, v9
	v_lshlrev_b32_e32 v30, 16, v4
	v_add_f32_e32 v1, 1.0, v1
	v_rcp_f32_e32 v22, v1
	v_add_f32_e32 v1, 1.0, v9
	v_rcp_f32_e32 v23, v1
	v_and_b32_e32 v31, 0xffff0000, v4
	v_pk_mul_f32 v[6:7], v[6:7], v[26:27]
	v_pk_mul_f32 v[24:25], v[10:11], v[10:11]
	v_pk_mul_f32 v[20:21], v[22:23], v[20:21]
	v_lshlrev_b32_e32 v22, 16, v8
	v_and_b32_e32 v23, 0xffff0000, v8
	v_mul_f32_e32 v1, 0xbfb8aa3b, v22
	v_exp_f32_e32 v1, v1
	v_mul_f32_e32 v5, 0xbfb8aa3b, v23
	v_exp_f32_e32 v5, v5
	v_pk_mul_f32 v[8:9], v[20:21], v[28:29]
	v_add_f32_e32 v1, 1.0, v1
	v_rcp_f32_e32 v20, v1
	v_add_f32_e32 v1, 1.0, v5
	v_rcp_f32_e32 v21, v1
	v_pk_mul_f32 v[28:29], v[8:9], v[8:9]
	v_pk_mul_f32 v[26:27], v[6:7], v[6:7]
	s_ashr_i32 s2, s18, 2
	v_pk_mul_f32 v[4:5], v[20:21], v[22:23]
	s_ashr_i32 s3, s2, 31
	v_pk_mul_f32 v[4:5], v[4:5], v[30:31]
	s_lshl_b64 s[2:3], s[2:3], 12
	v_pk_mul_f32 v[20:21], v[4:5], v[4:5]
	s_add_u32 s2, s14, s2
	v_add_f32_e32 v1, v20, v21
	v_add_f32_e32 v1, v28, v1
	v_add_f32_e32 v1, v29, v1
	v_add_f32_e32 v1, v26, v1
	v_add_f32_e32 v1, v27, v1
	v_add_f32_e32 v1, v24, v1
	v_add_f32_e32 v1, v25, v1
	s_nop 1
	v_add_f32_dpp v1, v1, v1 quad_perm:[1,0,3,2] row_mask:0xf bank_mask:0xf
	s_nop 1
	v_add_f32_dpp v1, v1, v1 quad_perm:[2,3,0,1] row_mask:0xf bank_mask:0xf
	s_nop 1
	v_add_f32_dpp v1, v1, v1 row_half_mirror row_mask:0xf bank_mask:0xf
	s_nop 1
	v_add_f32_dpp v1, v1, v1 row_mirror row_mask:0xf bank_mask:0xf
	s_nop 1
	v_add_f32_dpp v1, v1, v1 row_bcast:15 row_mask:0xa bank_mask:0xf
	s_nop 1
	v_add_f32_dpp v1, v1, v1 row_bcast:31 row_mask:0xc bank_mask:0xf
	s_nop 0
	v_readlane_b32 s32, v1, 63
	s_nop 1
	v_mov_b32_e32 v1, s32
	s_addc_u32 s3, s15, s3
	v_fmamk_f32 v1, v1, 0x3b000000, v228
	v_mul_f32_e32 v20, 0x4b800000, v1
	v_cmp_gt_f32_e32 vcc, s37, v1
	s_nop 1
	v_cndmask_b32_e32 v1, v1, v20, vcc
	v_rsq_f32_e32 v1, v1
	s_nop 0
	v_mul_f32_e32 v20, 0x45800000, v1
	v_cndmask_b32_e32 v20, v1, v20, vcc
	v_pk_mul_f32 v[4:5], v[4:5], v[20:21] op_sel_hi:[1,0]
	v_pk_mul_f32 v[8:9], v[8:9], v[20:21] op_sel_hi:[1,0]
	v_pk_mul_f32 v[4:5], v[64:65], v[4:5]
	v_pk_mul_f32 v[8:9], v[66:67], v[8:9]
	v_cvt_pk_bf16_f32 v4, v4, v5
	v_cvt_pk_bf16_f32 v5, v8, v9
	v_pk_mul_f32 v[6:7], v[6:7], v[20:21] op_sel_hi:[1,0]
	v_pk_mul_f32 v[8:9], v[10:11], v[20:21] op_sel_hi:[1,0]
	v_pk_mul_f32 v[6:7], v[68:69], v[6:7]
	v_pk_mul_f32 v[8:9], v[70:71], v[8:9]
	v_cvt_pk_bf16_f32 v6, v6, v7
	v_cvt_pk_bf16_f32 v7, v8, v9
	global_store_dwordx4 v0, v[4:7], s[2:3]
	s_branch .LBB0_115
